# S5 setup no longer carries two weight-conversion half items (picked up by later slots of the emitting pass)
# baseline (speedup 1.0000x reference)
.LBB0_655:
	s_lshl_b32 s6, s39, 3
	s_and_b32 s6, s6, 56
	s_bfe_u32 s8, s39, 0x30003
	s_or_b32 s80, s6, s8
	s_lshl_b32 s6, s39, 5
	s_and_b32 s6, s6, 0xfffff800
	s_waitcnt vmcnt(16)
	v_add_u32_e32 v2, s6, v143
	s_waitcnt vmcnt(13)
	v_ashrrev_i32_e32 v3, 31, v2
	v_lshlrev_b64 v[2:3], 12, v[2:3]
	v_lshl_add_u64 v[2:3], s[84:85], 0, v[2:3]
	s_lshl_b32 s6, s80, 5
	v_lshl_add_u64 v[130:131], v[2:3], 0, s[6:7]
	v_lshlrev_b32_e32 v76, 1, v96
	v_lshl_add_u64 v[2:3], v[130:131], 0, v[76:77]
	s_mov_b32 s6, 0x10000
	v_add_co_u32_e32 v4, vcc, s6, v2
	s_cmpk_lt_i32 s3, 0x6800
	s_waitcnt vmcnt(11)
	v_addc_co_u32_e32 v5, vcc, 0, v3, vcc
	v_add_co_u32_e32 v6, vcc, 0x20000, v2
	s_cselect_b64 s[90:91], -1, 0
	s_waitcnt vmcnt(9)
	v_addc_co_u32_e32 v7, vcc, 0, v3, vcc
	v_add_co_u32_e32 v8, vcc, 0x30000, v2
	s_cmpk_gt_i32 s3, 0x67ff
	s_waitcnt vmcnt(7)
	v_addc_co_u32_e32 v9, vcc, 0, v3, vcc
	global_load_dwordx2 v[118:119], v[2:3], off
	global_load_dwordx2 v[112:113], v[4:5], off
	global_load_dwordx2 v[114:115], v[6:7], off
	global_load_dwordx2 v[116:117], v[8:9], off
	v_lshlrev_b32_e32 v76, 2, v98
	s_branch .LBB0_657
	s_ashr_i32 s6, s3, 1
	s_cmpk_lt_u32 s6, 0x2c00
	s_cselect_b32 s8, s5, 0xe0
	s_cmpk_lt_i32 s6, 0x2c00
	s_cselect_b32 s24, s28, 0x800
	s_cselect_b32 s9, s29, 0xffffd400
	s_cmpk_lt_i32 s6, 0x1600
	s_cselect_b32 s8, 0xf0, s8
	s_cselect_b32 s9, 0, s9
	s_add_u32 s82, s0, s8
	s_addc_u32 s83, s1, 0
	s_add_i32 s9, s9, s6
	s_lshr_b32 s6, s24, 5
	s_abs_i32 s81, s6
	v_cvt_f32_u32_e32 v1, s81
	s_sub_i32 s86, 0, s81
	s_abs_i32 s25, s9
	s_xor_b32 s8, s9, s6
	v_rcp_iflag_f32_e32 v1, v1
	s_ashr_i32 s8, s8, 31
	s_load_dwordx2 s[82:83], s[82:83], 0x0
	v_mul_f32_e32 v1, 0x4f7ffffe, v1
	v_cvt_u32_f32_e32 v1, v1
	s_nop 0
	v_readfirstlane_b32 s87, v1
	s_mul_i32 s86, s86, s87
	s_mul_hi_u32 s86, s87, s86
	s_add_i32 s87, s87, s86
	s_mul_hi_u32 s86, s25, s87
	s_mul_i32 s87, s86, s81
	s_sub_i32 s25, s25, s87
	s_add_i32 s87, s86, 1
	s_sub_i32 s88, s25, s81
	s_cmp_ge_u32 s25, s81
	s_cselect_b32 s86, s87, s86
	s_cselect_b32 s25, s88, s25
	s_add_i32 s87, s86, 1
	s_cmp_ge_u32 s25, s81
	s_cselect_b32 s25, s87, s86
	s_xor_b32 s25, s25, s8
	s_sub_i32 s8, s25, s8
	s_mul_i32 s6, s8, s6
	s_sub_i32 s6, s9, s6
	s_lshl_b32 s9, s3, 5
	s_lshl_b32 s8, s8, 6
	s_and_b32 s9, s9, 32
	s_or_b32 s8, s8, s9
	v_or_b32_e32 v1, s8, v99
	s_lshl_b32 s88, s6, 5
	v_mad_i64_i32 v[2:3], s[92:93], v1, s24, 0
	s_waitcnt lgkmcnt(0)
	v_lshl_add_u64 v[2:3], v[2:3], 2, s[82:83]
	s_ashr_i32 s89, s88, 31
	v_lshl_add_u64 v[2:3], s[88:89], 2, v[2:3]
	v_lshl_add_u64 v[2:3], v[2:3], 0, v[76:77]
	s_lshl_b32 s6, s24, 3
	v_lshl_add_u64 v[4:5], v[2:3], 0, s[6:7]
	s_lshl_b32 s6, s24, 4
	global_load_dword v156, v[2:3], off nt
	global_load_dword v158, v[4:5], off nt
	v_lshl_add_u64 v[4:5], v[2:3], 0, s[6:7]
	s_mul_i32 s6, s24, 24
	global_load_dword v160, v[4:5], off nt
	v_lshl_add_u64 v[4:5], v[2:3], 0, s[6:7]
	s_lshl_b32 s6, s24, 5
	global_load_dword v163, v[4:5], off nt
	v_lshl_add_u64 v[4:5], v[2:3], 0, s[6:7]
	s_mul_i32 s6, s24, 40
	global_load_dword v166, v[4:5], off nt
	v_lshl_add_u64 v[4:5], v[2:3], 0, s[6:7]
	s_mul_i32 s6, s24, 48
	global_load_dword v165, v[4:5], off nt
	v_lshl_add_u64 v[4:5], v[2:3], 0, s[6:7]
	s_mul_i32 s6, s24, 56
	global_load_dword v168, v[4:5], off nt
	v_lshl_add_u64 v[4:5], v[2:3], 0, s[6:7]
	s_lshl_b32 s6, s24, 6
	global_load_dword v170, v[4:5], off nt
	v_lshl_add_u64 v[4:5], v[2:3], 0, s[6:7]
	s_mul_i32 s6, s24, 0x48
	global_load_dword v171, v[4:5], off nt
	v_lshl_add_u64 v[4:5], v[2:3], 0, s[6:7]
	s_mul_i32 s6, s24, 0x50
	global_load_dword v174, v[4:5], off nt
	v_lshl_add_u64 v[4:5], v[2:3], 0, s[6:7]
	s_mul_i32 s6, s24, 0x58
	global_load_dword v176, v[4:5], off nt
	v_lshl_add_u64 v[4:5], v[2:3], 0, s[6:7]
	s_mul_i32 s6, s24, 0x60
	global_load_dword v177, v[4:5], off nt
	v_lshl_add_u64 v[4:5], v[2:3], 0, s[6:7]
	s_mul_i32 s6, s24, 0x68
	global_load_dword v179, v[4:5], off nt
	v_lshl_add_u64 v[4:5], v[2:3], 0, s[6:7]
	s_mul_i32 s6, s24, 0x70
	global_load_dword v181, v[4:5], off nt
	v_lshl_add_u64 v[4:5], v[2:3], 0, s[6:7]
	s_mul_i32 s6, s24, 0x78
	v_lshl_add_u64 v[2:3], v[2:3], 0, s[6:7]
	global_load_dword v183, v[4:5], off nt
	global_load_dword v186, v[2:3], off nt
.LBB0_657:
	s_add_i32 s24, s3, s22
	s_cmpk_lt_i32 s24, 0x6800
	s_cselect_b64 s[92:93], -1, 0
	s_cmpk_gt_i32 s24, 0x67ff
	s_branch .LBB0_659
	s_ashr_i32 s6, s24, 1
	s_cmpk_lt_u32 s6, 0x2c00
	s_cselect_b32 s8, s5, 0xe0
	s_cmpk_lt_i32 s6, 0x2c00
	s_cselect_b32 s25, s28, 0x800
	s_cselect_b32 s9, s29, 0xffffd400
	s_cmpk_lt_i32 s6, 0x1600
	s_cselect_b32 s8, 0xf0, s8
	s_cselect_b32 s9, 0, s9
	s_add_u32 s82, s0, s8
	s_addc_u32 s83, s1, 0
	s_add_i32 s9, s9, s6
	s_lshr_b32 s6, s25, 5
	s_abs_i32 s86, s6
	v_cvt_f32_u32_e32 v1, s86
	s_sub_i32 s87, 0, s86
	s_abs_i32 s81, s9
	s_xor_b32 s8, s9, s6
	v_rcp_iflag_f32_e32 v1, v1
	s_ashr_i32 s8, s8, 31
	s_load_dwordx2 s[82:83], s[82:83], 0x0
	v_mul_f32_e32 v1, 0x4f7ffffe, v1
	v_cvt_u32_f32_e32 v1, v1
	s_nop 0
	v_readfirstlane_b32 s88, v1
	s_mul_i32 s87, s87, s88
	s_mul_hi_u32 s87, s88, s87
	s_add_i32 s88, s88, s87
	s_mul_hi_u32 s87, s81, s88
	s_mul_i32 s88, s87, s86
	s_sub_i32 s81, s81, s88
	s_add_i32 s88, s87, 1
	s_sub_i32 s89, s81, s86
	s_cmp_ge_u32 s81, s86
	s_cselect_b32 s87, s88, s87
	s_cselect_b32 s81, s89, s81
	s_add_i32 s88, s87, 1
	s_cmp_ge_u32 s81, s86
	s_cselect_b32 s81, s88, s87
	s_xor_b32 s81, s81, s8
	s_sub_i32 s8, s81, s8
	s_mul_i32 s6, s8, s6
	s_sub_i32 s6, s9, s6
	s_lshl_b32 s9, s3, 5
	s_lshl_b32 s8, s8, 6
	s_and_b32 s9, s9, 32
	s_or_b32 s8, s8, s9
	v_or_b32_e32 v1, s8, v99
	s_lshl_b32 s88, s6, 5
	v_mad_i64_i32 v[2:3], vcc, v1, s25, 0
	s_waitcnt lgkmcnt(0)
	v_lshl_add_u64 v[2:3], v[2:3], 2, s[82:83]
	s_ashr_i32 s89, s88, 31
	v_lshl_add_u64 v[2:3], s[88:89], 2, v[2:3]
	v_lshl_add_u64 v[2:3], v[2:3], 0, v[76:77]
	s_lshl_b32 s6, s25, 3
	v_lshl_add_u64 v[4:5], v[2:3], 0, s[6:7]
	s_lshl_b32 s6, s25, 4
	global_load_dword v155, v[2:3], off nt
	global_load_dword v157, v[4:5], off nt
	v_lshl_add_u64 v[4:5], v[2:3], 0, s[6:7]
	s_mul_i32 s6, s25, 24
	global_load_dword v159, v[4:5], off nt
	v_lshl_add_u64 v[4:5], v[2:3], 0, s[6:7]
	s_lshl_b32 s6, s25, 5
	global_load_dword v161, v[4:5], off nt
	v_lshl_add_u64 v[4:5], v[2:3], 0, s[6:7]
	s_mul_i32 s6, s25, 40
	global_load_dword v164, v[4:5], off nt
	v_lshl_add_u64 v[4:5], v[2:3], 0, s[6:7]
	s_mul_i32 s6, s25, 48
	global_load_dword v167, v[4:5], off nt
	v_lshl_add_u64 v[4:5], v[2:3], 0, s[6:7]
	s_mul_i32 s6, s25, 56
	global_load_dword v169, v[4:5], off nt
	v_lshl_add_u64 v[4:5], v[2:3], 0, s[6:7]
	s_lshl_b32 s6, s25, 6
	global_load_dword v172, v[4:5], off nt
	v_lshl_add_u64 v[4:5], v[2:3], 0, s[6:7]
	s_mul_i32 s6, s25, 0x48
	global_load_dword v173, v[4:5], off nt
	v_lshl_add_u64 v[4:5], v[2:3], 0, s[6:7]
	s_mul_i32 s6, s25, 0x50
	global_load_dword v175, v[4:5], off nt
	v_lshl_add_u64 v[4:5], v[2:3], 0, s[6:7]
	s_mul_i32 s6, s25, 0x58
	global_load_dword v178, v[4:5], off nt
	v_lshl_add_u64 v[4:5], v[2:3], 0, s[6:7]
	s_mul_i32 s6, s25, 0x60
	global_load_dword v180, v[4:5], off nt
	v_lshl_add_u64 v[4:5], v[2:3], 0, s[6:7]
	s_mul_i32 s6, s25, 0x68
	global_load_dword v182, v[4:5], off nt
	v_lshl_add_u64 v[4:5], v[2:3], 0, s[6:7]
	s_mul_i32 s6, s25, 0x70
	global_load_dword v184, v[4:5], off nt
	v_lshl_add_u64 v[4:5], v[2:3], 0, s[6:7]
	s_mul_i32 s6, s25, 0x78
	v_lshl_add_u64 v[2:3], v[2:3], 0, s[6:7]
	global_load_dword v185, v[4:5], off nt
	global_load_dword v187, v[2:3], off nt
.LBB0_659:
	s_lshl_b32 s6, s80, 10
	s_lshl_b32 s81, s80, 4
	v_or_b32_e32 v1, s6, v135
	s_add_u32 s82, s94, s6
	v_lshlrev_b32_e32 v2, 2, v1
	v_mov_b32_e32 v3, v77
	s_addc_u32 s83, s95, 0
	v_lshlrev_b32_e32 v120, 2, v162
	v_lshl_add_u64 v[4:5], v[78:79], 0, v[2:3]
	v_lshl_add_u64 v[2:3], v[80:81], 0, v[2:3]
	v_or_b32_e32 v1, s6, v137
	global_load_dword v110, v120, s[82:83]
	global_load_dword v108, v120, s[82:83] offset:256
	global_load_dwordx4 v[70:73], v[2:3], off
	v_lshlrev_b32_e32 v2, 2, v1
	v_mov_b32_e32 v3, v77
	global_load_dwordx4 v[66:69], v[4:5], off
	v_lshl_add_u64 v[4:5], v[78:79], 0, v[2:3]
	v_lshl_add_u64 v[2:3], v[80:81], 0, v[2:3]
	v_or_b32_e32 v1, s6, v139
	global_load_dwordx4 v[58:61], v[4:5], off
	global_load_dwordx4 v[62:65], v[2:3], off
	global_load_dword v146, v148, s[82:83] offset:512
	global_load_dword v144, v148, s[82:83] offset:768
	global_load_dword v142, v148, s[82:83] offset:576
	global_load_dword v140, v148, s[82:83] offset:832
	global_load_dword v136, v148, s[82:83] offset:896
	global_load_dword v138, v148, s[82:83] offset:640
	v_lshlrev_b32_e32 v2, 2, v1
	v_mov_b32_e32 v3, v77
	v_lshl_add_u64 v[4:5], v[78:79], 0, v[2:3]
	v_lshl_add_u64 v[2:3], v[80:81], 0, v[2:3]
	v_lshlrev_b32_e32 v1, 2, v102
	global_load_dwordx4 v[50:53], v[4:5], off
	global_load_dwordx4 v[54:57], v[2:3], off
	global_load_dword v134, v1, s[82:83] offset:512
	global_load_dword v132, v1, s[82:83] offset:768
	v_or_b32_e32 v1, s6, v141
	v_lshlrev_b32_e32 v2, 2, v1
	v_mov_b32_e32 v3, v77
	v_lshl_add_u64 v[4:5], v[78:79], 0, v[2:3]
	v_lshl_add_u64 v[2:3], v[80:81], 0, v[2:3]
	v_or_b32_e32 v1, s81, v74
	global_load_dwordx4 v[46:49], v[2:3], off
	v_lshlrev_b32_e32 v2, 8, v1
	v_or_b32_e32 v1, s81, v96
	v_lshlrev_b32_e32 v1, 4, v1
	v_mov_b32_e32 v3, v77
	v_or_b32_e32 v18, v1, v74
	v_or_b32_e32 v1, v1, v102
	global_load_dwordx4 v[42:45], v[4:5], off
	v_lshl_add_u64 v[4:5], v[82:83], 0, v[2:3]
	v_lshl_add_u64 v[6:7], v[84:85], 0, v[2:3]
	v_lshlrev_b32_e32 v18, 2, v18
	v_lshlrev_b32_e32 v19, 2, v1
	s_lshl_b32 s88, s81, 2
	s_mov_b32 s89, s7
	global_load_dwordx4 v[34:37], v[4:5], off offset:16
	global_load_dwordx4 v[38:41], v[4:5], off
	global_load_dwordx4 v[26:29], v[4:5], off offset:144
	global_load_dwordx4 v[30:33], v[4:5], off offset:128
	global_load_dwordx4 v[10:13], v[6:7], off offset:16
	global_load_dwordx4 v[14:17], v[6:7], off
	s_nop 0
	global_load_dwordx4 v[2:5], v[6:7], off offset:144
	s_nop 0
	global_load_dwordx4 v[6:9], v[6:7], off offset:128
	s_nop 0
	global_load_dword v1, v18, s[10:11]
	global_load_dword v191, v18, s[10:11] offset:64
	global_load_dword v192, v18, s[10:11] offset:128
	global_load_dword v193, v19, s[10:11]
	v_lshl_add_u64 v[18:19], v[86:87], 0, s[88:89]
	global_load_dwordx4 v[22:25], v[18:19], off
	v_lshl_add_u64 v[18:19], v[88:89], 0, s[88:89]
	global_load_dwordx4 v[18:21], v[18:19], off
	s_andn2_b64 vcc, exec, s[90:91]
	v_add_u32_e32 v121, 0x400, v152
	v_add_u32_e32 v188, 0x800, v152
	v_add_u32_e32 v189, 0xc00, v152
	v_lshlrev_b32_e32 v122, 1, v100
	s_branch .LBB0_661
	s_ashr_i32 s6, s3, 1
	s_add_i32 s8, s6, 0xffffea00
	s_cmpk_gt_i32 s6, 0x2bff
	s_cselect_b32 s9, 64, 0xb0
	v_cvt_f32_ubyte0_e32 v107, s9
	v_rcp_iflag_f32_e32 v107, v107
	s_cselect_b32 s25, 0xffffd400, s29
	s_cmpk_gt_i32 s6, 0x15ff
	s_cselect_b32 s25, s25, 0
	v_mul_f32_e32 v107, 0x4f7ffffe, v107
	v_cvt_u32_f32_e32 v107, v107
	s_sub_i32 s86, 0, s9
	s_add_i32 s25, s25, s6
	s_abs_i32 s83, s25
	v_readfirstlane_b32 s87, v107
	s_mul_i32 s86, s86, s87
	s_mul_hi_u32 s86, s87, s86
	s_add_i32 s87, s87, s86
	s_mul_hi_u32 s86, s83, s87
	s_mul_i32 s87, s86, s9
	s_sub_i32 s83, s83, s87
	s_ashr_i32 s82, s25, 31
	s_add_i32 s87, s86, 1
	s_sub_i32 s89, s83, s9
	s_cmp_ge_u32 s83, s9
	s_cselect_b32 s86, s87, s86
	s_cselect_b32 s83, s89, s83
	s_add_i32 s87, s86, 1
	s_cmp_ge_u32 s83, s9
	s_cselect_b32 s83, s87, s86
	s_xor_b32 s83, s83, s82
	s_sub_i32 s82, s83, s82
	s_mul_i32 s9, s82, s9
	s_sub_i32 s9, s25, s9
	s_lshl_b32 s25, s9, 5
	s_lshl_b32 s9, s9, 6
	s_and_b32 s9, s9, 0xffffff00
	s_and_b32 s83, s25, 0x60
	s_cmpk_lt_u32 s8, 0x1600
	s_cselect_b32 s8, 0x80, 0
	s_or_b32 s8, s83, s8
	s_or_b32 s8, s8, s9
	s_cmpk_gt_i32 s6, 0x2bff
	s_cselect_b32 s6, s42, 0x4200000
	s_cselect_b32 s8, s25, s8
	s_add_u32 s6, s18, s6
	s_addc_u32 s9, s19, 0
	s_lshl_b32 s25, s3, 5
	s_waitcnt vmcnt(46)
	ds_write2_b32 v152, v156, v158 offset1:66
	s_waitcnt vmcnt(44)
	ds_write2_b32 v152, v160, v163 offset0:132 offset1:198
	s_waitcnt vmcnt(42)
	ds_write2_b32 v121, v166, v165 offset0:8 offset1:74
	s_waitcnt vmcnt(40)
	ds_write2_b32 v121, v168, v170 offset0:140 offset1:206
	s_waitcnt vmcnt(38)
	ds_write2_b32 v188, v171, v174 offset0:16 offset1:82
	s_waitcnt vmcnt(36)
	ds_write2_b32 v188, v176, v177 offset0:148 offset1:214
	s_waitcnt vmcnt(34)
	ds_write2_b32 v189, v179, v181 offset0:24 offset1:90
	s_waitcnt vmcnt(32)
	ds_write2_b32 v189, v183, v186 offset0:156 offset1:222
	s_and_b32 s25, s25, 32
	s_lshl_b32 s82, s82, 6
	s_or_b32 s82, s82, s25
	s_waitcnt lgkmcnt(0)
	s_ashr_i32 s83, s82, 31
	ds_read2_b32 v[194:195], v103 offset1:16
	ds_read2_b32 v[196:197], v103 offset0:33 offset1:49
	ds_read2_b32 v[198:199], v103 offset0:66 offset1:82
	ds_read2_b32 v[200:201], v103 offset0:99 offset1:115
	ds_read2_b32 v[202:203], v103 offset0:132 offset1:148
	ds_read2_b32 v[204:205], v103 offset0:165 offset1:181
	ds_read2_b32 v[206:207], v103 offset0:198 offset1:214
	ds_read2_b32 v[208:209], v103 offset0:231 offset1:247
	s_lshl_b64 s[82:83], s[82:83], 1
	s_add_u32 s82, s6, s82
	v_or_b32_e32 v210, s8, v101
	s_addc_u32 s83, s9, s83
	v_mov_b32_e32 v123, v77
	v_ashrrev_i32_e32 v211, 31, v210
	v_lshl_add_u64 v[128:129], s[82:83], 0, v[122:123]
	v_lshlrev_b64 v[210:211], 12, v[210:211]
	s_waitcnt lgkmcnt(6)
	v_cvt_pk_bf16_f32 v124, v194, v196
	s_waitcnt lgkmcnt(4)
	v_cvt_pk_bf16_f32 v125, v198, v200
	s_waitcnt lgkmcnt(2)
	v_cvt_pk_bf16_f32 v126, v202, v204
	s_waitcnt lgkmcnt(0)
	v_cvt_pk_bf16_f32 v127, v206, v208
	v_lshl_add_u64 v[210:211], v[128:129], 0, v[210:211]
	v_or_b32_e32 v194, s8, v133
	global_store_dwordx4 v[210:211], v[124:127], off
	s_nop 1
	v_cvt_pk_bf16_f32 v124, v195, v197
	v_ashrrev_i32_e32 v195, 31, v194
	v_lshlrev_b64 v[194:195], 12, v[194:195]
	v_cvt_pk_bf16_f32 v125, v199, v201
	v_cvt_pk_bf16_f32 v126, v203, v205
	v_cvt_pk_bf16_f32 v127, v207, v209
	v_lshl_add_u64 v[128:129], v[128:129], 0, v[194:195]
	global_store_dwordx4 v[128:129], v[124:127], off
	s_waitcnt lgkmcnt(0)
.LBB0_661:
	s_andn2_b64 vcc, exec, s[92:93]
	s_branch .LBB0_663
	s_ashr_i32 s6, s24, 1
	s_add_i32 s8, s6, 0xffffea00
	s_cmpk_gt_i32 s6, 0x2bff
	s_cselect_b32 s9, 64, 0xb0
	v_cvt_f32_ubyte0_e32 v107, s9
	v_rcp_iflag_f32_e32 v107, v107
	s_cselect_b32 s24, 0xffffd400, s29
	s_cmpk_gt_i32 s6, 0x15ff
	s_cselect_b32 s24, s24, 0
	v_mul_f32_e32 v107, 0x4f7ffffe, v107
	v_cvt_u32_f32_e32 v107, v107
	s_sub_i32 s83, 0, s9
	s_add_i32 s24, s24, s6
	s_abs_i32 s82, s24
	v_readfirstlane_b32 s86, v107
	s_mul_i32 s83, s83, s86
	s_mul_hi_u32 s83, s86, s83
	s_add_i32 s86, s86, s83
	s_mul_hi_u32 s83, s82, s86
	s_mul_i32 s86, s83, s9
	s_sub_i32 s82, s82, s86
	s_ashr_i32 s25, s24, 31
	s_add_i32 s86, s83, 1
	s_sub_i32 s87, s82, s9
	s_cmp_ge_u32 s82, s9
	s_cselect_b32 s83, s86, s83
	s_cselect_b32 s82, s87, s82
	s_add_i32 s86, s83, 1
	s_cmp_ge_u32 s82, s9
	s_cselect_b32 s82, s86, s83
	s_xor_b32 s82, s82, s25
	s_sub_i32 s25, s82, s25
	s_mul_i32 s9, s25, s9
	s_sub_i32 s9, s24, s9
	s_lshl_b32 s24, s9, 5
	s_lshl_b32 s9, s9, 6
	s_and_b32 s9, s9, 0xffffff00
	s_and_b32 s82, s24, 0x60
	s_cmpk_lt_u32 s8, 0x1600
	s_cselect_b32 s8, 0x80, 0
	s_or_b32 s8, s82, s8
	s_or_b32 s8, s8, s9
	s_cmpk_gt_i32 s6, 0x2bff
	s_cselect_b32 s6, s42, 0x4200000
	s_cselect_b32 s8, s24, s8
	s_add_u32 s6, s18, s6
	s_addc_u32 s9, s19, 0
	s_lshl_b32 s24, s3, 5
	s_waitcnt vmcnt(46)
	ds_write2_b32 v152, v155, v157 offset1:66
	s_waitcnt vmcnt(44)
	ds_write2_b32 v152, v159, v161 offset0:132 offset1:198
	s_waitcnt vmcnt(42)
	ds_write2_b32 v121, v164, v167 offset0:8 offset1:74
	s_waitcnt vmcnt(40)
	ds_write2_b32 v121, v169, v172 offset0:140 offset1:206
	s_waitcnt vmcnt(38)
	ds_write2_b32 v188, v173, v175 offset0:16 offset1:82
	s_waitcnt vmcnt(36)
	ds_write2_b32 v188, v178, v180 offset0:148 offset1:214
	s_waitcnt vmcnt(34)
	ds_write2_b32 v189, v182, v184 offset0:24 offset1:90
	s_waitcnt vmcnt(32)
	ds_write2_b32 v189, v185, v187 offset0:156 offset1:222
	s_and_b32 s24, s24, 32
	s_lshl_b32 s25, s25, 6
	s_or_b32 s24, s25, s24
	s_waitcnt lgkmcnt(0)
	s_ashr_i32 s25, s24, 31
	ds_read2_b32 v[194:195], v103 offset1:16
	ds_read2_b32 v[196:197], v103 offset0:33 offset1:49
	ds_read2_b32 v[198:199], v103 offset0:66 offset1:82
	ds_read2_b32 v[200:201], v103 offset0:99 offset1:115
	ds_read2_b32 v[202:203], v103 offset0:132 offset1:148
	ds_read2_b32 v[204:205], v103 offset0:165 offset1:181
	ds_read2_b32 v[206:207], v103 offset0:198 offset1:214
	ds_read2_b32 v[208:209], v103 offset0:231 offset1:247
	s_lshl_b64 s[24:25], s[24:25], 1
	s_add_u32 s24, s6, s24
	v_or_b32_e32 v210, s8, v101
	s_addc_u32 s25, s9, s25
	v_mov_b32_e32 v123, v77
	v_ashrrev_i32_e32 v211, 31, v210
	v_lshl_add_u64 v[128:129], s[24:25], 0, v[122:123]
	v_lshlrev_b64 v[210:211], 12, v[210:211]
	s_waitcnt lgkmcnt(6)
	v_cvt_pk_bf16_f32 v124, v194, v196
	s_waitcnt lgkmcnt(4)
	v_cvt_pk_bf16_f32 v125, v198, v200
	s_waitcnt lgkmcnt(2)
	v_cvt_pk_bf16_f32 v126, v202, v204
	s_waitcnt lgkmcnt(0)
	v_cvt_pk_bf16_f32 v127, v206, v208
	v_lshl_add_u64 v[210:211], v[128:129], 0, v[210:211]
	v_or_b32_e32 v194, s8, v133
	global_store_dwordx4 v[210:211], v[124:127], off
	s_nop 1
	v_cvt_pk_bf16_f32 v124, v195, v197
	v_ashrrev_i32_e32 v195, 31, v194
	v_lshlrev_b64 v[194:195], 12, v[194:195]
	v_cvt_pk_bf16_f32 v125, v199, v201
	v_cvt_pk_bf16_f32 v126, v203, v205
	v_cvt_pk_bf16_f32 v127, v207, v209
	v_lshl_add_u64 v[128:129], v[128:129], 0, v[194:195]
	global_store_dwordx4 v[128:129], v[124:127], off
	s_waitcnt lgkmcnt(0)
.LBB0_663:
	s_mov_b32 s89, s3
	s_cmpk_lt_i32 s89, 0x6800
	s_cselect_b64 vcc, -1, 0
	s_cmpk_gt_i32 s89, 0x67ff
	s_cbranch_scc1 .LBB0_665
	s_ashr_i32 s6, s89, 1
	s_cmpk_lt_u32 s6, 0x2c00
	s_cselect_b32 s8, s5, 0xe0
	s_cmpk_lt_i32 s6, 0x2c00
	s_cselect_b32 s24, s28, 0x800
	s_cselect_b32 s9, s29, 0xffffd400
	s_cmpk_lt_i32 s6, 0x1600
	s_cselect_b32 s8, 0xf0, s8
	s_cselect_b32 s9, 0, s9
	s_add_u32 s82, s0, s8
	s_addc_u32 s83, s1, 0
	s_add_i32 s9, s9, s6
	s_lshr_b32 s6, s24, 5
	s_abs_i32 s86, s6
	v_cvt_f32_u32_e32 v107, s86
	s_sub_i32 s87, 0, s86
	s_abs_i32 s25, s9
	s_xor_b32 s8, s9, s6
	v_rcp_iflag_f32_e32 v107, v107
	s_ashr_i32 s8, s8, 31
	s_load_dwordx2 s[82:83], s[82:83], 0x0
	v_mul_f32_e32 v107, 0x4f7ffffe, v107
	v_cvt_u32_f32_e32 v107, v107
	s_nop 0
	v_readfirstlane_b32 s90, v107
	s_mul_i32 s87, s87, s90
	s_mul_hi_u32 s87, s90, s87
	s_add_i32 s90, s90, s87
	s_mul_hi_u32 s87, s25, s90
	s_mul_i32 s90, s87, s86
	s_sub_i32 s25, s25, s90
	s_add_i32 s90, s87, 1
	s_sub_i32 s91, s25, s86
	s_cmp_ge_u32 s25, s86
	s_cselect_b32 s87, s90, s87
	s_cselect_b32 s25, s91, s25
	s_add_i32 s90, s87, 1
	s_cmp_ge_u32 s25, s86
	s_cselect_b32 s25, s90, s87
	s_xor_b32 s25, s25, s8
	s_sub_i32 s8, s25, s8
	s_mul_i32 s6, s8, s6
	s_sub_i32 s6, s9, s6
	s_lshl_b32 s9, s3, 5
	s_lshl_b32 s8, s8, 6
	s_and_b32 s9, s9, 32
	s_or_b32 s8, s8, s9
	v_or_b32_e32 v107, s8, v99
	s_lshl_b32 s90, s6, 5
	v_mad_i64_i32 v[124:125], s[92:93], v107, s24, 0
	s_waitcnt lgkmcnt(0)
	v_lshl_add_u64 v[124:125], v[124:125], 2, s[82:83]
	s_ashr_i32 s91, s90, 31
	v_lshl_add_u64 v[124:125], s[90:91], 2, v[124:125]
	v_lshl_add_u64 v[124:125], v[124:125], 0, v[76:77]
	s_lshl_b32 s6, s24, 3
	v_lshl_add_u64 v[126:127], v[124:125], 0, s[6:7]
	s_lshl_b32 s6, s24, 4
	global_load_dword v156, v[124:125], off nt
	global_load_dword v158, v[126:127], off nt
	v_lshl_add_u64 v[126:127], v[124:125], 0, s[6:7]
	s_mul_i32 s6, s24, 24
	global_load_dword v160, v[126:127], off nt
	v_lshl_add_u64 v[126:127], v[124:125], 0, s[6:7]
	s_lshl_b32 s6, s24, 5
	global_load_dword v163, v[126:127], off nt
	v_lshl_add_u64 v[126:127], v[124:125], 0, s[6:7]
	s_mul_i32 s6, s24, 40
	global_load_dword v166, v[126:127], off nt
	v_lshl_add_u64 v[126:127], v[124:125], 0, s[6:7]
	s_mul_i32 s6, s24, 48
	global_load_dword v165, v[126:127], off nt
	v_lshl_add_u64 v[126:127], v[124:125], 0, s[6:7]
	s_mul_i32 s6, s24, 56
	global_load_dword v168, v[126:127], off nt
	v_lshl_add_u64 v[126:127], v[124:125], 0, s[6:7]
	s_lshl_b32 s6, s24, 6
	global_load_dword v170, v[126:127], off nt
	v_lshl_add_u64 v[126:127], v[124:125], 0, s[6:7]
	s_mul_i32 s6, s24, 0x48
	global_load_dword v171, v[126:127], off nt
	v_lshl_add_u64 v[126:127], v[124:125], 0, s[6:7]
	s_mul_i32 s6, s24, 0x50
	global_load_dword v174, v[126:127], off nt
	v_lshl_add_u64 v[126:127], v[124:125], 0, s[6:7]
	s_mul_i32 s6, s24, 0x58
	global_load_dword v176, v[126:127], off nt
	v_lshl_add_u64 v[126:127], v[124:125], 0, s[6:7]
	s_mul_i32 s6, s24, 0x60
	global_load_dword v177, v[126:127], off nt
	v_lshl_add_u64 v[126:127], v[124:125], 0, s[6:7]
	s_mul_i32 s6, s24, 0x68
	global_load_dword v179, v[126:127], off nt
	v_lshl_add_u64 v[126:127], v[124:125], 0, s[6:7]
	s_mul_i32 s6, s24, 0x70
	global_load_dword v181, v[126:127], off nt
	v_lshl_add_u64 v[126:127], v[124:125], 0, s[6:7]
	s_mul_i32 s6, s24, 0x78
	v_lshl_add_u64 v[124:125], v[124:125], 0, s[6:7]
	global_load_dword v183, v[126:127], off nt
	global_load_dword v186, v[124:125], off nt
